# attention phase B: last 32-key step stages and loads only the 16 key rows that can be valid; no register-stage loads once no step is left
# speedup vs baseline: 1.0112x; 1.0100x over previous
.LBB0_546:
	s_cmp_eq_u32 s77, 1
	s_cselect_b32 s0, 2, 4
	s_lshr_b32 s1, 16, s0
	s_lshl_b32 s18, s67, 6
	s_cmp_lg_u32 s77, 2
	s_cbranch_scc1 .Lat_full1
	s_cmp_lg_u32 s67, 2
	s_cbranch_scc1 .Lat_full1
	s_waitcnt vmcnt(0) lgkmcnt(2)
	ds_write_b128 v219, v[12:15]
	ds_write_b128 v219, v[24:27] offset:1152
	ds_write_b128 v220, v[4:7] offset:9216
	ds_write_b128 v220, v[8:11] offset:10240
	s_branch .Lat_done1
.Lat_full1:
	s_waitcnt vmcnt(14) lgkmcnt(2)
	ds_write_b128 v219, v[12:15]
	s_waitcnt vmcnt(12)
	ds_write_b128 v219, v[24:27] offset:1152
	s_waitcnt vmcnt(10)
	ds_write_b128 v219, v[32:35] offset:2304
	s_waitcnt vmcnt(8)
	ds_write_b128 v219, v[40:43] offset:3456
	s_waitcnt vmcnt(6)
	ds_write_b128 v219, v[52:55] offset:4608
	s_waitcnt vmcnt(4)
	ds_write_b128 v219, v[64:67] offset:5760
	s_waitcnt vmcnt(2)
	ds_write_b128 v219, v[76:79] offset:6912
	s_waitcnt vmcnt(0)
	ds_write_b128 v219, v[88:91] offset:8064
	s_waitcnt lgkmcnt(8)
	ds_write_b128 v220, v[4:7] offset:9216
	ds_write_b128 v220, v[8:11] offset:10240
	ds_write_b128 v220, v[16:19] offset:11264
	ds_write_b128 v220, v[20:23] offset:12288
	ds_write_b128 v220, v[28:31] offset:13312
	ds_write_b128 v220, v[36:39] offset:14336
	ds_write_b128 v220, v[44:47] offset:15360
	ds_write_b128 v220, v[68:71] offset:16384
.Lat_done1:
	s_setprio 1
	v_mul_u32_u24_e32 v2, s1, v173
	s_sub_i32 s16, 0x80, s18
	s_lshr_b32 s0, s8, s0
	v_mov_b32_e32 v3, s16
	s_sub_i32 s19, s16, s0
	v_subrev_u32_e32 v2, s18, v2
	v_add_u32_e32 v228, v207, v192
	v_add_u32_e32 v230, v207, v194
	v_mad_u32_u24 v18, s1, v173, v3
	s_cmp_lg_u32 s77, 2
	v_max_i32_e32 v19, s19, v2
	v_add_u32_e32 v229, v207, v193
	ds_read_b128 v[10:13], v228 offset:9216
	ds_read_b128 v[14:17], v229 offset:9216
	v_add_u32_e32 v231, v207, v195
	ds_read_b128 v[6:9], v230 offset:9728
	ds_read_b128 v[2:5], v231 offset:9728
	s_cselect_b64 s[0:1], -1, 0
	s_cmp_lg_u32 s67, 2
	s_cselect_b64 s[16:17], -1, 0
	s_or_b64 s[0:1], s[16:17], s[0:1]
	v_sub_u32_e32 v18, v18, v19
	v_sub_u32_e32 v25, v176, v19
	s_mov_b64 s[16:17], -1
	s_and_b64 vcc, exec, s[0:1]
	v_add_u32_e32 v225, s45, v175
	v_cmp_le_u32_e64 s[0:1], v25, v18
	v_add_u32_e32 v26, 1, v25
	v_add_u32_e32 v24, 2, v25
	v_add_u32_e32 v23, 3, v25
	v_add_u32_e32 v22, 4, v25
	v_add_u32_e32 v21, 5, v25
	v_add_u32_e32 v20, 6, v25
	v_add_u32_e32 v19, 7, v25
	s_cbranch_vccz .LBB0_548
	s_waitcnt vmcnt(1) lgkmcnt(3)
	v_mfma_f32_16x16x32_bf16 v[28:31], v[10:13], v[132:135], 0
	ds_read_b128 v[32:35], v228 offset:13312
	ds_read_b128 v[36:39], v229 offset:13312
	v_cmp_le_u32_e32 vcc, v26, v18
	ds_read_b128 v[40:43], v230 offset:13824
	ds_read_b128 v[44:47], v231 offset:13824
	s_waitcnt vmcnt(0) lgkmcnt(6)
	v_mfma_f32_16x16x32_bf16 v[28:31], v[14:17], v[136:139], v[28:31]
	s_mov_b64 s[16:17], 0
	s_waitcnt lgkmcnt(5)
	v_mfma_f32_16x16x32_bf16 v[52:55], v[6:9], v[132:135], 0
	s_waitcnt lgkmcnt(4)
	v_mfma_f32_16x16x32_bf16 v[52:55], v[2:5], v[136:139], v[52:55]
	s_nop 2
	v_cndmask_b32_e32 v64, v217, v29, vcc
	v_cmp_le_u32_e32 vcc, v24, v18
	v_cndmask_b32_e64 v27, v217, v28, s[0:1]
	s_nop 0
	v_cndmask_b32_e32 v65, v217, v30, vcc
	v_cmp_le_u32_e32 vcc, v23, v18
	s_nop 1
	v_cndmask_b32_e32 v66, v217, v31, vcc
	s_waitcnt lgkmcnt(3)
	v_mfma_f32_16x16x32_bf16 v[28:31], v[32:35], v[132:135], 0
	v_cmp_le_u32_e32 vcc, v22, v18
	s_nop 1
	v_cndmask_b32_e32 v52, v217, v52, vcc
	v_cmp_le_u32_e32 vcc, v21, v18
	s_waitcnt lgkmcnt(2)
	v_mfma_f32_16x16x32_bf16 v[28:31], v[36:39], v[136:139], v[28:31]
	v_add_u32_e32 v37, 32, v25
	v_cndmask_b32_e32 v53, v217, v53, vcc
	v_cmp_le_u32_e32 vcc, v20, v18
	s_waitcnt lgkmcnt(1)
	v_mfma_f32_16x16x32_bf16 v[32:35], v[40:43], v[132:135], 0
	v_cndmask_b32_e32 v54, v217, v54, vcc
	v_cmp_le_u32_e32 vcc, v19, v18
	s_waitcnt lgkmcnt(0)
	v_mfma_f32_16x16x32_bf16 v[32:35], v[44:47], v[136:139], v[32:35]
	v_cndmask_b32_e32 v36, v217, v55, vcc
	v_cmp_le_u32_e32 vcc, v37, v18
	v_add_u32_e32 v37, 33, v25
	s_nop 0
	v_cndmask_b32_e32 v28, v217, v28, vcc
	v_cmp_le_u32_e32 vcc, v37, v18
	v_add_u32_e32 v37, 34, v25
	s_nop 0
	v_cndmask_b32_e32 v29, v217, v29, vcc
	v_cmp_le_u32_e32 vcc, v37, v18
	v_add_u32_e32 v37, 35, v25
	s_nop 0
	v_cndmask_b32_e32 v30, v217, v30, vcc
	v_cmp_le_u32_e32 vcc, v37, v18
	v_add_u32_e32 v37, 36, v25
	s_nop 0
	v_cndmask_b32_e32 v31, v217, v31, vcc
	v_cmp_le_u32_e32 vcc, v37, v18
	v_add_u32_e32 v37, 37, v25
	s_nop 0
	v_cndmask_b32_e32 v32, v217, v32, vcc
	v_cmp_le_u32_e32 vcc, v37, v18
	v_add_u32_e32 v37, 38, v25
	s_nop 0
	v_cndmask_b32_e32 v33, v217, v33, vcc
	v_cmp_le_u32_e32 vcc, v37, v18
	v_add_u32_e32 v37, 39, v25
	s_nop 0
	v_cndmask_b32_e32 v34, v217, v34, vcc
	v_cmp_le_u32_e32 vcc, v37, v18
	v_max3_f32 v37, v27, s62, v64
	v_max3_f32 v37, v37, v65, v66
	v_max3_f32 v37, v37, v52, v53
	v_max3_f32 v37, v37, v54, v36
	v_max3_f32 v37, v37, v28, v29
	v_max3_f32 v37, v37, v30, v31
	v_cndmask_b32_e32 v35, v217, v35, vcc
	v_max3_f32 v37, v37, v32, v33
	v_max3_f32 v37, v37, v34, v35
	ds_bpermute_b32 v38, v0, v37
	s_waitcnt lgkmcnt(0)
	v_max_f32_e32 v38, v38, v38
	v_max_f32_e32 v37, v37, v38
	ds_bpermute_b32 v38, v222, v37
	s_waitcnt lgkmcnt(0)
	v_max3_f32 v226, v223, v37, v38
	v_sub_f32_e32 v27, v27, v226
	v_exp_f32_e32 v27, v27
	v_sub_f32_e32 v38, v64, v226
	v_exp_f32_e32 v38, v38
	v_sub_f32_e32 v39, v65, v226
	v_sub_f32_e32 v28, v28, v226
	v_exp_f32_e32 v39, v39
	v_sub_f32_e32 v40, v66, v226
	v_exp_f32_e32 v90, v28
	v_sub_f32_e32 v28, v29, v226
	v_exp_f32_e32 v40, v40
	v_sub_f32_e32 v42, v52, v226
	v_exp_f32_e32 v91, v28
	v_sub_f32_e32 v28, v30, v226
	v_add_f32_e32 v41, 0, v27
	v_exp_f32_e32 v42, v42
	v_sub_f32_e32 v43, v53, v226
	v_exp_f32_e32 v156, v28
	v_sub_f32_e32 v28, v31, v226
	v_add_f32_e32 v41, v38, v41
	v_exp_f32_e32 v43, v43
	v_sub_f32_e32 v44, v54, v226
	v_exp_f32_e32 v160, v28
	v_sub_f32_e32 v28, v32, v226
	v_add_f32_e32 v41, v39, v41
	v_exp_f32_e32 v44, v44
	v_sub_f32_e32 v36, v36, v226
	v_exp_f32_e32 v161, v28
	v_sub_f32_e32 v28, v33, v226
	v_sub_f32_e32 v37, v223, v226
	v_add_f32_e32 v41, v40, v41
	v_exp_f32_e32 v36, v36
	v_exp_f32_e32 v162, v28
	v_sub_f32_e32 v28, v34, v226
	v_add_f32_e32 v41, v42, v41
	v_exp_f32_e32 v164, v28
	v_sub_f32_e32 v64, v35, v226
	v_exp_f32_e32 v88, v37
	v_cvt_pk_bf16_f32 v28, v27, v38
	v_cvt_pk_bf16_f32 v29, v39, v40
	v_cvt_pk_bf16_f32 v30, v42, v43
	v_cvt_pk_bf16_f32 v31, v44, v36
	ds_read_b64_tr_b16 v[34:35], v225 offset:576
	ds_read_b64_tr_b16 v[32:33], v225
	v_add_f32_e32 v41, v43, v41
	v_add_f32_e32 v41, v44, v41
	v_add_f32_e32 v89, v36, v41
	ds_read_b64_tr_b16 v[42:43], v225 offset:608
	ds_read_b64_tr_b16 v[40:41], v225 offset:32
	ds_read_b64_tr_b16 v[44:45], v225 offset:64
	ds_read_b64_tr_b16 v[52:53], v225 offset:96
	ds_read_b64_tr_b16 v[46:47], v225 offset:640
	ds_read_b64_tr_b16 v[54:55], v225 offset:672
	v_pk_mul_f32 v[38:39], v[154:155], v[88:89] op_sel_hi:[1,0]
	v_pk_mul_f32 v[36:37], v[152:153], v[88:89] op_sel_hi:[1,0]
	v_exp_f32_e32 v27, v64
	v_pk_mul_f32 v[66:67], v[142:143], v[88:89] op_sel_hi:[1,0]
	s_waitcnt lgkmcnt(6)
	v_mfma_f32_16x16x32_bf16 v[32:35], v[32:35], v[28:31], v[36:39]
	v_mul_f32_e64 v64, v140, v88
	v_mul_f32_e64 v65, v141, v88
	s_nop 0
	v_pk_mul_f32 v[38:39], v[150:151], v[88:89] op_sel_hi:[1,0]
	v_pk_mul_f32 v[36:37], v[148:149], v[88:89] op_sel_hi:[1,0]
	s_waitcnt lgkmcnt(4)
	s_nop 0
	v_mfma_f32_16x16x32_bf16 v[36:39], v[40:43], v[28:31], v[36:39]
	v_mul_f32_e64 v42, v146, v88
	v_mul_f32_e64 v43, v147, v88
	v_pk_mul_f32 v[40:41], v[144:145], v[88:89] op_sel_hi:[1,0]
	s_waitcnt lgkmcnt(1)
	s_nop 0
	v_mfma_f32_16x16x32_bf16 v[40:43], v[44:47], v[28:31], v[40:43]
	v_cvt_pk_bf16_f32 v44, v90, v91
	v_cvt_pk_bf16_f32 v45, v156, v160
	v_cvt_pk_bf16_f32 v46, v161, v162
	v_cvt_pk_bf16_f32 v47, v164, v27
	ds_read_b64_tr_b16 v[70:71], v225 offset:5184
	ds_read_b64_tr_b16 v[68:69], v225 offset:4608
	s_waitcnt lgkmcnt(0)
	v_mfma_f32_16x16x32_bf16 v[168:171], v[68:71], v[44:47], v[32:35]
	s_nop 2
	v_add_f32_e32 v32, v90, v89
	v_add_f32_e32 v32, v91, v32
	v_add_f32_e32 v32, v156, v32
	v_mfma_f32_16x16x32_bf16 v[28:31], v[52:55], v[28:31], v[64:67]
	ds_read_b64_tr_b16 v[54:55], v225 offset:5216
	ds_read_b64_tr_b16 v[52:53], v225 offset:4640
	s_nop 0
	ds_read_b64_tr_b16 v[64:65], v225 offset:4672
	ds_read_b64_tr_b16 v[76:77], v225 offset:4704
	ds_read_b64_tr_b16 v[66:67], v225 offset:5248
	ds_read_b64_tr_b16 v[78:79], v225 offset:5280
	v_add_f32_e32 v32, v160, v32
	v_add_f32_e32 v32, v161, v32
	v_add_f32_e32 v32, v162, v32
	s_waitcnt lgkmcnt(0)
	v_add_f32_e32 v32, v164, v32
	v_add_f32_e32 v227, v27, v32
	s_waitcnt lgkmcnt(4)
	v_mfma_f32_16x16x32_bf16 v[156:159], v[52:55], v[44:47], v[36:39]
	v_fmac_f32_e32 v227, v224, v88
	s_waitcnt lgkmcnt(1)
	v_mfma_f32_16x16x32_bf16 v[160:163], v[64:67], v[44:47], v[40:43]
	s_waitcnt lgkmcnt(0)
	v_mfma_f32_16x16x32_bf16 v[164:167], v[76:79], v[44:47], v[28:31]

.LBB0_550:
	s_setprio 0
	s_cmp_lt_i32 s67, 2
	s_cselect_b64 s[18:19], -1, 0
	s_cmp_lt_i32 s77, 2
	s_cselect_b64 s[38:39], -1, 0
	s_or_b64 s[16:17], s[18:19], s[38:39]
	s_mov_b64 s[0:1], -1
	v_readfirstlane_b32 s81, v0
	v_readfirstlane_b32 s82, v0
	v_readfirstlane_b32 s79, v0
	s_andn2_b64 vcc, exec, s[16:17]
	v_readfirstlane_b32 s80, v0
	s_cbranch_vccnz .LBB0_544
	s_cmp_eq_u32 s75, 3
	s_cbranch_scc0 .Lrl_do1
	s_mov_b64 s[16:17], 0
	s_waitcnt lgkmcnt(0)
	s_branch .Lrl_tail1
.Lrl_do1:
	s_cmp_eq_u32 s75, 1
	s_cselect_b32 s0, 2, 4
	s_lshr_b32 s16, s8, s0
	s_lshl_b32 s17, s76, 6
	s_lshr_b32 s1, 0x800, s0
	s_add_i32 s16, s16, s17
	s_add_i32 s1, s1, -1
	v_add_u32_e32 v68, s16, v191
	s_waitcnt lgkmcnt(0)
	v_min_i32_e32 v2, s1, v68
	v_cmp_lt_i32_e32 vcc, -1, v68
	s_lshl_b32 s20, -1, s0
	s_andn2_b32 s20, s8, s20
	v_cndmask_b32_e32 v2, 0, v2, vcc
	v_lshlrev_b32_e32 v2, s0, v2
	v_add_u32_e32 v2, s20, v2
	v_lshl_or_b32 v2, v2, 6, v180
	v_ashrrev_i32_e32 v3, 31, v2
	v_lshlrev_b64 v[2:3], 1, v[2:3]
	v_lshl_add_u64 v[4:5], s[10:11], 0, v[2:3]
	v_lshl_add_u64 v[2:3], s[12:13], 0, v[2:3]
	global_load_dwordx4 v[4:7], v[4:5], off
	s_nop 0
	global_load_dwordx4 v[12:15], v[2:3], off
	v_add_u32_e32 v2, 8, v68
	v_min_i32_e32 v3, s1, v2
	v_cmp_lt_i32_e32 vcc, -1, v2
	s_mov_b64 s[16:17], 0
	s_nop 0
	v_cndmask_b32_e32 v2, 0, v3, vcc
	v_lshlrev_b32_e32 v2, s0, v2
	v_add_u32_e32 v2, s20, v2
	v_lshl_or_b32 v2, v2, 6, v180
	v_ashrrev_i32_e32 v3, 31, v2
	v_lshlrev_b64 v[2:3], 1, v[2:3]
	v_lshl_add_u64 v[8:9], s[10:11], 0, v[2:3]
	v_lshl_add_u64 v[2:3], s[12:13], 0, v[2:3]
	global_load_dwordx4 v[8:11], v[8:9], off
	s_nop 0
	global_load_dwordx4 v[24:27], v[2:3], off
	s_cmp_lg_u32 s75, 2
	s_cbranch_scc1 .Lrl_full1
	s_waitcnt lgkmcnt(0)
	s_cmp_eq_u32 s76, 2
	s_cbranch_scc1 .Lrl_tail1
.Lrl_full1:
	v_add_u32_e32 v2, 16, v68
	v_min_i32_e32 v3, s1, v2
	v_cmp_lt_i32_e32 vcc, -1, v2
	s_nop 1
	v_cndmask_b32_e32 v2, 0, v3, vcc
	v_lshlrev_b32_e32 v2, s0, v2
	v_add_u32_e32 v2, s20, v2
	v_lshl_or_b32 v2, v2, 6, v180
	v_ashrrev_i32_e32 v3, 31, v2
	v_lshlrev_b64 v[2:3], 1, v[2:3]
	v_lshl_add_u64 v[16:17], s[10:11], 0, v[2:3]
	v_lshl_add_u64 v[2:3], s[12:13], 0, v[2:3]
	global_load_dwordx4 v[16:19], v[16:17], off
	s_nop 0
	global_load_dwordx4 v[32:35], v[2:3], off
	v_add_u32_e32 v2, 24, v68
	v_min_i32_e32 v3, s1, v2
	v_cmp_lt_i32_e32 vcc, -1, v2
	s_nop 1
	v_cndmask_b32_e32 v2, 0, v3, vcc
	v_lshlrev_b32_e32 v2, s0, v2
	v_add_u32_e32 v2, s20, v2
	v_lshl_or_b32 v2, v2, 6, v180
	v_ashrrev_i32_e32 v3, 31, v2
	v_lshlrev_b64 v[2:3], 1, v[2:3]
	v_lshl_add_u64 v[20:21], s[10:11], 0, v[2:3]
	v_lshl_add_u64 v[2:3], s[12:13], 0, v[2:3]
	global_load_dwordx4 v[20:23], v[20:21], off
	s_nop 0
	global_load_dwordx4 v[40:43], v[2:3], off
	v_add_u32_e32 v2, 32, v68
	v_min_i32_e32 v3, s1, v2
	v_cmp_lt_i32_e32 vcc, -1, v2
	s_nop 1
	v_cndmask_b32_e32 v2, 0, v3, vcc
	v_lshlrev_b32_e32 v2, s0, v2
	v_add_u32_e32 v2, s20, v2
	v_lshl_or_b32 v2, v2, 6, v180
	v_ashrrev_i32_e32 v3, 31, v2
	v_lshlrev_b64 v[2:3], 1, v[2:3]
	v_lshl_add_u64 v[28:29], s[10:11], 0, v[2:3]
	v_lshl_add_u64 v[2:3], s[12:13], 0, v[2:3]
	global_load_dwordx4 v[28:31], v[28:29], off
	s_nop 0
	global_load_dwordx4 v[52:55], v[2:3], off
	v_add_u32_e32 v2, 40, v68
	v_min_i32_e32 v3, s1, v2
	v_cmp_lt_i32_e32 vcc, -1, v2
	s_nop 1
	v_cndmask_b32_e32 v2, 0, v3, vcc
	v_lshlrev_b32_e32 v2, s0, v2
	v_add_u32_e32 v2, s20, v2
	v_lshl_or_b32 v2, v2, 6, v180
	v_ashrrev_i32_e32 v3, 31, v2
	v_lshlrev_b64 v[2:3], 1, v[2:3]
	v_lshl_add_u64 v[36:37], s[10:11], 0, v[2:3]
	v_lshl_add_u64 v[2:3], s[12:13], 0, v[2:3]
	global_load_dwordx4 v[36:39], v[36:37], off
	s_nop 0
	global_load_dwordx4 v[64:67], v[2:3], off
	v_add_u32_e32 v2, 48, v68
	v_min_i32_e32 v3, s1, v2
	v_cmp_lt_i32_e32 vcc, -1, v2
	s_nop 1
	v_cndmask_b32_e32 v2, 0, v3, vcc
	v_lshlrev_b32_e32 v2, s0, v2
	v_add_u32_e32 v2, s20, v2
	v_lshl_or_b32 v2, v2, 6, v180
	v_ashrrev_i32_e32 v3, 31, v2
	v_lshlrev_b64 v[2:3], 1, v[2:3]
	v_lshl_add_u64 v[44:45], s[10:11], 0, v[2:3]
	v_lshl_add_u64 v[2:3], s[12:13], 0, v[2:3]
	global_load_dwordx4 v[44:47], v[44:45], off
	s_nop 0
	global_load_dwordx4 v[76:79], v[2:3], off
	v_add_u32_e32 v2, 56, v68
	v_min_i32_e32 v3, s1, v2
	v_cmp_lt_i32_e32 vcc, -1, v2
	s_nop 1
	v_cndmask_b32_e32 v2, 0, v3, vcc
	v_lshlrev_b32_e32 v2, s0, v2
	v_add_u32_e32 v2, s20, v2
	v_lshl_or_b32 v2, v2, 6, v180
	v_ashrrev_i32_e32 v3, 31, v2
	v_lshlrev_b64 v[2:3], 1, v[2:3]
	v_lshl_add_u64 v[68:69], s[10:11], 0, v[2:3]
	v_lshl_add_u64 v[2:3], s[12:13], 0, v[2:3]
	global_load_dwordx4 v[68:71], v[68:69], off
	s_nop 0
	global_load_dwordx4 v[88:91], v[2:3], off
.Lrl_tail1:
	s_andn2_b64 vcc, exec, s[14:15]
	s_cbranch_vccnz .LBB0_555
	s_add_i32 s0, s76, 1
	s_cmp_lt_i32 s76, 2
	s_mov_b64 s[16:17], -1
	s_cbranch_scc1 .LBB0_554
	s_add_i32 s1, s75, 1
	s_cmp_lt_i32 s75, 2
	s_cselect_b64 s[16:17], -1, 0
	s_and_b64 s[14:15], s[16:17], exec
	s_cselect_b32 s0, s66, s0
	s_mov_b32 s75, s1

.LBB0_555:
	s_add_i32 s67, s67, 1
	s_and_b64 s[0:1], s[38:39], exec
	s_cselect_b32 s14, s66, s67
	s_and_b64 s[0:1], s[18:19], exec
	s_cselect_b32 s78, s67, s14
	s_xor_b64 s[0:1], s[18:19], -1
	v_cndmask_b32_e64 v2, 0, 1, s[0:1]
	s_waitcnt vmcnt(32)
	ds_write_b128 v219, v[48:51]
	s_waitcnt vmcnt(30)
	ds_write_b128 v219, v[60:63] offset:1152
	s_cmp_eq_u64 s[18:19], 0
	s_addc_u32 s99, s77, 0
	s_cmp_lg_u32 s99, 2
	s_cbranch_scc1 .Lat_full2
	s_cmp_lg_u32 s78, 2
	s_cbranch_scc1 .Lat_full2
	ds_write_b128 v220, v[56:59] offset:9216
	ds_write_b128 v220, v[72:75] offset:10240
	s_waitcnt vmcnt(18)
	s_setprio 1
	s_branch .Lat_done2
.Lat_full2:
	s_waitcnt vmcnt(28)
	ds_write_b128 v219, v[80:83] offset:2304
	s_waitcnt vmcnt(26)
	ds_write_b128 v219, v[92:95] offset:3456
	s_waitcnt vmcnt(24)
	ds_write_b128 v219, v[100:103] offset:4608
	s_waitcnt vmcnt(22)
	ds_write_b128 v219, v[108:111] offset:5760
	s_waitcnt vmcnt(20)
	ds_write_b128 v219, v[116:119] offset:6912
	s_waitcnt vmcnt(18)
	ds_write_b128 v219, v[124:127] offset:8064
	ds_write_b128 v220, v[56:59] offset:9216
	ds_write_b128 v220, v[72:75] offset:10240
	ds_write_b128 v220, v[84:87] offset:11264
	ds_write_b128 v220, v[96:99] offset:12288
	ds_write_b128 v220, v[104:107] offset:13312
	ds_write_b128 v220, v[112:115] offset:14336
	ds_write_b128 v220, v[120:123] offset:15360
	s_setprio 1
	ds_write_b128 v220, v[128:131] offset:16384
.Lat_done2:
	v_readfirstlane_b32 s0, v2
	s_add_i32 s67, s77, s0
	s_cmp_eq_u32 s67, 1
	s_cselect_b32 s0, 2, 4
	s_lshl_b32 s20, s78, 6
	s_lshr_b32 s1, 16, s0
	s_sub_i32 s18, 0x80, s20
	s_lshr_b32 s0, s8, s0
	ds_read_b128 v[60:63], v228 offset:9216
	ds_read_b128 v[72:75], v229 offset:9216
	ds_read_b128 v[56:59], v230 offset:9728
	ds_read_b128 v[48:51], v231 offset:9728
	s_sub_i32 s21, s18, s0
	v_mul_u32_u24_e32 v2, s1, v173
	v_mov_b32_e32 v3, s18
	s_cmp_lg_u32 s67, 2
	v_mad_u32_u24 v3, s1, v173, v3
	s_cselect_b64 s[0:1], -1, 0
	s_cmp_lg_u32 s78, 2
	v_subrev_u32_e32 v2, s20, v2
	s_cselect_b64 s[18:19], -1, 0
	v_max_i32_e32 v80, s21, v2
	s_or_b64 s[0:1], s[0:1], s[18:19]
	v_sub_u32_e32 v2, v3, v80
	v_sub_u32_e32 v85, v176, v80
	s_mov_b64 s[14:15], -1
	s_and_b64 vcc, exec, s[0:1]
	v_cmp_le_u32_e64 s[0:1], v85, v2
	v_add_u32_e32 v86, 1, v85
	v_add_u32_e32 v84, 2, v85
	v_add_u32_e32 v83, 3, v85
	v_add_u32_e32 v82, 4, v85
	v_add_u32_e32 v81, 5, v85
	v_add_u32_e32 v80, 6, v85
	v_add_u32_e32 v3, 7, v85
	s_cbranch_vccz .LBB0_557
	s_waitcnt vmcnt(17) lgkmcnt(3)
	v_mfma_f32_16x16x32_bf16 v[92:95], v[60:63], v[132:135], 0
	ds_read_b128 v[96:99], v228 offset:13312
	ds_read_b128 v[100:103], v229 offset:13312
	v_cmp_le_u32_e32 vcc, v86, v2
	ds_read_b128 v[104:107], v230 offset:13824
	ds_read_b128 v[108:111], v231 offset:13824
	s_waitcnt vmcnt(16) lgkmcnt(6)
	v_mfma_f32_16x16x32_bf16 v[92:95], v[72:75], v[136:139], v[92:95]
	s_mov_b64 s[14:15], 0
	s_waitcnt lgkmcnt(5)
	v_mfma_f32_16x16x32_bf16 v[112:115], v[56:59], v[132:135], 0
	s_waitcnt lgkmcnt(4)
	v_mfma_f32_16x16x32_bf16 v[112:115], v[48:51], v[136:139], v[112:115]
	s_nop 2
	v_cndmask_b32_e32 v116, v217, v93, vcc
	v_cmp_le_u32_e32 vcc, v84, v2
	v_cndmask_b32_e64 v87, v217, v92, s[0:1]
	s_nop 0
	v_cndmask_b32_e32 v117, v217, v94, vcc
	v_cmp_le_u32_e32 vcc, v83, v2
	s_nop 1
	v_cndmask_b32_e32 v118, v217, v95, vcc
	s_waitcnt lgkmcnt(3)
	v_mfma_f32_16x16x32_bf16 v[92:95], v[96:99], v[132:135], 0
	v_cmp_le_u32_e32 vcc, v82, v2
	s_nop 1
	v_cndmask_b32_e32 v112, v217, v112, vcc
	v_cmp_le_u32_e32 vcc, v81, v2
	s_waitcnt lgkmcnt(2)
	v_mfma_f32_16x16x32_bf16 v[92:95], v[100:103], v[136:139], v[92:95]
	v_add_u32_e32 v101, 32, v85
	v_cndmask_b32_e32 v113, v217, v113, vcc
	v_cmp_le_u32_e32 vcc, v80, v2
	s_waitcnt lgkmcnt(1)
	v_mfma_f32_16x16x32_bf16 v[96:99], v[104:107], v[132:135], 0
	v_cndmask_b32_e32 v114, v217, v114, vcc
	v_cmp_le_u32_e32 vcc, v3, v2
	s_waitcnt lgkmcnt(0)
	v_mfma_f32_16x16x32_bf16 v[96:99], v[108:111], v[136:139], v[96:99]
	v_cndmask_b32_e32 v100, v217, v115, vcc
	v_cmp_le_u32_e32 vcc, v101, v2
	v_add_u32_e32 v101, 33, v85
	s_nop 0
	v_cndmask_b32_e32 v92, v217, v92, vcc
	v_cmp_le_u32_e32 vcc, v101, v2
	v_add_u32_e32 v101, 34, v85
	s_nop 0
	v_cndmask_b32_e32 v93, v217, v93, vcc
	v_cmp_le_u32_e32 vcc, v101, v2
	v_add_u32_e32 v101, 35, v85
	s_nop 0
	v_cndmask_b32_e32 v94, v217, v94, vcc
	v_cmp_le_u32_e32 vcc, v101, v2
	v_add_u32_e32 v101, 36, v85
	s_nop 0
	v_cndmask_b32_e32 v95, v217, v95, vcc
	v_cmp_le_u32_e32 vcc, v101, v2
	v_add_u32_e32 v101, 37, v85
	s_nop 0
	v_cndmask_b32_e32 v96, v217, v96, vcc
	v_cmp_le_u32_e32 vcc, v101, v2
	v_add_u32_e32 v101, 38, v85
	s_nop 0
	v_cndmask_b32_e32 v97, v217, v97, vcc
	v_cmp_le_u32_e32 vcc, v101, v2
	v_add_u32_e32 v101, 39, v85
	s_nop 0
	v_cndmask_b32_e32 v98, v217, v98, vcc
	v_cmp_le_u32_e32 vcc, v101, v2
	v_max3_f32 v101, v87, s62, v116
	v_max3_f32 v101, v101, v117, v118
	v_max3_f32 v101, v101, v112, v113
	v_max3_f32 v101, v101, v114, v100
	v_max3_f32 v101, v101, v92, v93
	v_max3_f32 v101, v101, v94, v95
	v_cndmask_b32_e32 v99, v217, v99, vcc
	v_max3_f32 v101, v101, v96, v97
	v_max3_f32 v101, v101, v98, v99
	ds_bpermute_b32 v102, v0, v101
	s_waitcnt lgkmcnt(0)
	v_max_f32_e32 v102, v102, v102
	v_max_f32_e32 v101, v101, v102
	ds_bpermute_b32 v102, v222, v101
	s_waitcnt lgkmcnt(0)
	v_max3_f32 v223, v226, v101, v102
	v_sub_f32_e32 v87, v87, v223
	v_exp_f32_e32 v87, v87
	v_sub_f32_e32 v102, v116, v223
	v_exp_f32_e32 v102, v102
	v_sub_f32_e32 v103, v117, v223
	v_sub_f32_e32 v92, v92, v223
	v_exp_f32_e32 v103, v103
	v_sub_f32_e32 v104, v118, v223
	v_exp_f32_e32 v130, v92
	v_sub_f32_e32 v92, v93, v223
	v_exp_f32_e32 v104, v104
	v_sub_f32_e32 v106, v112, v223
	v_exp_f32_e32 v131, v92
	v_sub_f32_e32 v92, v94, v223
	v_add_f32_e32 v105, 0, v87
	v_exp_f32_e32 v106, v106
	v_sub_f32_e32 v107, v113, v223
	v_exp_f32_e32 v140, v92
	v_sub_f32_e32 v92, v95, v223
	v_add_f32_e32 v105, v102, v105
	v_exp_f32_e32 v107, v107
	v_sub_f32_e32 v108, v114, v223
	v_exp_f32_e32 v141, v92
	v_sub_f32_e32 v92, v96, v223
	v_add_f32_e32 v105, v103, v105
	v_exp_f32_e32 v108, v108
	v_sub_f32_e32 v100, v100, v223
	v_exp_f32_e32 v142, v92
	v_sub_f32_e32 v92, v97, v223
	v_sub_f32_e32 v101, v226, v223
	v_add_f32_e32 v105, v104, v105
	v_exp_f32_e32 v100, v100
	v_exp_f32_e32 v143, v92
	v_sub_f32_e32 v92, v98, v223
	v_add_f32_e32 v105, v106, v105
	v_exp_f32_e32 v224, v92
	v_sub_f32_e32 v116, v99, v223
	v_exp_f32_e32 v128, v101
	v_cvt_pk_bf16_f32 v92, v87, v102
	v_cvt_pk_bf16_f32 v93, v103, v104
	v_cvt_pk_bf16_f32 v94, v106, v107
	v_cvt_pk_bf16_f32 v95, v108, v100
	ds_read_b64_tr_b16 v[98:99], v225 offset:576
	ds_read_b64_tr_b16 v[96:97], v225
	v_add_f32_e32 v105, v107, v105
	v_add_f32_e32 v105, v108, v105
	v_add_f32_e32 v129, v100, v105
	ds_read_b64_tr_b16 v[106:107], v225 offset:608
	ds_read_b64_tr_b16 v[104:105], v225 offset:32
	ds_read_b64_tr_b16 v[108:109], v225 offset:64
	ds_read_b64_tr_b16 v[112:113], v225 offset:96
	ds_read_b64_tr_b16 v[110:111], v225 offset:640
	ds_read_b64_tr_b16 v[114:115], v225 offset:672
	v_pk_mul_f32 v[102:103], v[170:171], v[128:129] op_sel_hi:[1,0]
	v_pk_mul_f32 v[100:101], v[168:169], v[128:129] op_sel_hi:[1,0]
	v_exp_f32_e32 v87, v116
	v_pk_mul_f32 v[118:119], v[166:167], v[128:129] op_sel_hi:[1,0]
	s_waitcnt lgkmcnt(6)
	v_mfma_f32_16x16x32_bf16 v[96:99], v[96:99], v[92:95], v[100:103]
	v_mul_f32_e64 v116, v164, v128
	v_mul_f32_e64 v117, v165, v128
	s_nop 0
	v_pk_mul_f32 v[102:103], v[158:159], v[128:129] op_sel_hi:[1,0]
	v_pk_mul_f32 v[100:101], v[156:157], v[128:129] op_sel_hi:[1,0]
	s_waitcnt lgkmcnt(4)
	s_nop 0
	v_mfma_f32_16x16x32_bf16 v[100:103], v[104:107], v[92:95], v[100:103]
	v_mul_f32_e64 v106, v162, v128
	v_mul_f32_e64 v107, v163, v128
	v_pk_mul_f32 v[104:105], v[160:161], v[128:129] op_sel_hi:[1,0]
	s_waitcnt lgkmcnt(1)
	s_nop 0
	v_mfma_f32_16x16x32_bf16 v[104:107], v[108:111], v[92:95], v[104:107]
	v_cvt_pk_bf16_f32 v108, v130, v131
	v_cvt_pk_bf16_f32 v109, v140, v141
	v_cvt_pk_bf16_f32 v110, v142, v143
	v_cvt_pk_bf16_f32 v111, v224, v87
	ds_read_b64_tr_b16 v[122:123], v225 offset:5184
	ds_read_b64_tr_b16 v[120:121], v225 offset:4608
	s_waitcnt lgkmcnt(0)
	v_mfma_f32_16x16x32_bf16 v[152:155], v[120:123], v[108:111], v[96:99]
	s_nop 2
	v_add_f32_e32 v96, v130, v129
	v_add_f32_e32 v96, v131, v96
	v_add_f32_e32 v96, v140, v96
	v_mfma_f32_16x16x32_bf16 v[92:95], v[112:115], v[92:95], v[116:119]
	ds_read_b64_tr_b16 v[114:115], v225 offset:5216
	ds_read_b64_tr_b16 v[112:113], v225 offset:4640
	s_nop 0
	ds_read_b64_tr_b16 v[116:117], v225 offset:4672
	ds_read_b64_tr_b16 v[124:125], v225 offset:4704
	ds_read_b64_tr_b16 v[118:119], v225 offset:5248
	ds_read_b64_tr_b16 v[126:127], v225 offset:5280
	v_add_f32_e32 v96, v141, v96
	v_add_f32_e32 v96, v142, v96
	v_add_f32_e32 v96, v143, v96
	s_waitcnt lgkmcnt(0)
	v_add_f32_e32 v96, v224, v96
	v_add_f32_e32 v224, v87, v96
	s_waitcnt lgkmcnt(4)
	v_mfma_f32_16x16x32_bf16 v[148:151], v[112:115], v[108:111], v[100:103]
	v_fmac_f32_e32 v224, v227, v128
	s_waitcnt lgkmcnt(1)
	v_mfma_f32_16x16x32_bf16 v[144:147], v[116:119], v[108:111], v[104:107]
	s_waitcnt lgkmcnt(0)
	v_mfma_f32_16x16x32_bf16 v[140:143], v[124:127], v[108:111], v[92:95]

.LBB0_559:
	s_setprio 0
	s_cmp_lt_i32 s78, 2
	s_cselect_b64 s[18:19], -1, 0
	s_cmp_lt_i32 s67, 2
	s_cselect_b64 s[38:39], -1, 0
	s_or_b64 s[14:15], s[18:19], s[38:39]
	s_mov_b64 s[0:1], -1
	v_readfirstlane_b32 s81, v0
	v_readfirstlane_b32 s82, v0
	v_readfirstlane_b32 s79, v0
	s_andn2_b64 vcc, exec, s[14:15]
	v_readfirstlane_b32 s80, v0
	s_cbranch_vccnz .LBB0_545
	s_cmp_eq_u32 s75, 3
	s_cbranch_scc0 .Lrl_do2
	s_waitcnt lgkmcnt(0)
	s_branch .Lrl_tail2
.Lrl_do2:
	s_cmp_eq_u32 s75, 1
	s_cselect_b32 s0, 2, 4
	s_lshr_b32 s14, s8, s0
	s_lshl_b32 s15, s76, 6
	s_lshr_b32 s1, 0x800, s0
	s_add_i32 s14, s14, s15
	s_add_i32 s1, s1, -1
	v_add_u32_e32 v124, s14, v191
	v_min_i32_e32 v2, s1, v124
	v_cmp_lt_i32_e32 vcc, -1, v124
	s_lshl_b32 s20, -1, s0
	s_andn2_b32 s20, s8, s20
	v_cndmask_b32_e32 v2, 0, v2, vcc
	v_lshlrev_b32_e32 v2, s0, v2
	v_add_u32_e32 v2, s20, v2
	v_lshl_or_b32 v2, v2, 6, v180
	v_ashrrev_i32_e32 v3, 31, v2
	v_lshlrev_b64 v[2:3], 1, v[2:3]
	s_waitcnt lgkmcnt(0)
	v_lshl_add_u64 v[48:49], s[10:11], 0, v[2:3]
	v_lshl_add_u64 v[2:3], s[12:13], 0, v[2:3]
	global_load_dwordx4 v[56:59], v[48:49], off
	s_nop 0
	global_load_dwordx4 v[48:51], v[2:3], off
	v_add_u32_e32 v2, 8, v124
	v_min_i32_e32 v3, s1, v2
	v_cmp_lt_i32_e32 vcc, -1, v2
	s_nop 1
	v_cndmask_b32_e32 v2, 0, v3, vcc
	v_lshlrev_b32_e32 v2, s0, v2
	v_add_u32_e32 v2, s20, v2
	v_lshl_or_b32 v2, v2, 6, v180
	v_ashrrev_i32_e32 v3, 31, v2
	v_lshlrev_b64 v[2:3], 1, v[2:3]
	v_lshl_add_u64 v[60:61], s[10:11], 0, v[2:3]
	v_lshl_add_u64 v[2:3], s[12:13], 0, v[2:3]
	global_load_dwordx4 v[72:75], v[60:61], off
	s_nop 0
	global_load_dwordx4 v[60:63], v[2:3], off
	s_cmp_lg_u32 s75, 2
	s_cbranch_scc1 .Lrl_full2
	s_waitcnt lgkmcnt(0)
	s_cmp_eq_u32 s76, 2
	s_cbranch_scc1 .Lrl_tail2
.Lrl_full2:
	v_add_u32_e32 v2, 16, v124
	v_min_i32_e32 v3, s1, v2
	v_cmp_lt_i32_e32 vcc, -1, v2
	s_nop 1
	v_cndmask_b32_e32 v2, 0, v3, vcc
	v_lshlrev_b32_e32 v2, s0, v2
	v_add_u32_e32 v2, s20, v2
	v_lshl_or_b32 v2, v2, 6, v180
	v_ashrrev_i32_e32 v3, 31, v2
	v_lshlrev_b64 v[2:3], 1, v[2:3]
	v_lshl_add_u64 v[80:81], s[10:11], 0, v[2:3]
	v_lshl_add_u64 v[2:3], s[12:13], 0, v[2:3]
	global_load_dwordx4 v[84:87], v[80:81], off
	s_nop 0
	global_load_dwordx4 v[80:83], v[2:3], off
	v_add_u32_e32 v2, 24, v124
	v_min_i32_e32 v3, s1, v2
	v_cmp_lt_i32_e32 vcc, -1, v2
	s_nop 1
	v_cndmask_b32_e32 v2, 0, v3, vcc
	v_lshlrev_b32_e32 v2, s0, v2
	v_add_u32_e32 v2, s20, v2
	v_lshl_or_b32 v2, v2, 6, v180
	v_ashrrev_i32_e32 v3, 31, v2
	v_lshlrev_b64 v[2:3], 1, v[2:3]
	v_lshl_add_u64 v[92:93], s[10:11], 0, v[2:3]
	v_lshl_add_u64 v[2:3], s[12:13], 0, v[2:3]
	global_load_dwordx4 v[96:99], v[92:93], off
	s_nop 0
	global_load_dwordx4 v[92:95], v[2:3], off
	v_add_u32_e32 v2, 32, v124
	v_min_i32_e32 v3, s1, v2
	v_cmp_lt_i32_e32 vcc, -1, v2
	s_nop 1
	v_cndmask_b32_e32 v2, 0, v3, vcc
	v_lshlrev_b32_e32 v2, s0, v2
	v_add_u32_e32 v2, s20, v2
	v_lshl_or_b32 v2, v2, 6, v180
	v_ashrrev_i32_e32 v3, 31, v2
	v_lshlrev_b64 v[2:3], 1, v[2:3]
	v_lshl_add_u64 v[100:101], s[10:11], 0, v[2:3]
	v_lshl_add_u64 v[2:3], s[12:13], 0, v[2:3]
	global_load_dwordx4 v[104:107], v[100:101], off
	s_nop 0
	global_load_dwordx4 v[100:103], v[2:3], off
	v_add_u32_e32 v2, 40, v124
	v_min_i32_e32 v3, s1, v2
	v_cmp_lt_i32_e32 vcc, -1, v2
	s_nop 1
	v_cndmask_b32_e32 v2, 0, v3, vcc
	v_lshlrev_b32_e32 v2, s0, v2
	v_add_u32_e32 v2, s20, v2
	v_lshl_or_b32 v2, v2, 6, v180
	v_ashrrev_i32_e32 v3, 31, v2
	v_lshlrev_b64 v[2:3], 1, v[2:3]
	v_lshl_add_u64 v[108:109], s[10:11], 0, v[2:3]
	v_lshl_add_u64 v[2:3], s[12:13], 0, v[2:3]
	global_load_dwordx4 v[112:115], v[108:109], off
	s_nop 0
	global_load_dwordx4 v[108:111], v[2:3], off
	v_add_u32_e32 v2, 48, v124
	v_min_i32_e32 v3, s1, v2
	v_cmp_lt_i32_e32 vcc, -1, v2
	s_nop 1
	v_cndmask_b32_e32 v2, 0, v3, vcc
	v_lshlrev_b32_e32 v2, s0, v2
	v_add_u32_e32 v2, s20, v2
	v_lshl_or_b32 v2, v2, 6, v180
	v_ashrrev_i32_e32 v3, 31, v2
	v_lshlrev_b64 v[2:3], 1, v[2:3]
	v_lshl_add_u64 v[116:117], s[10:11], 0, v[2:3]
	v_lshl_add_u64 v[2:3], s[12:13], 0, v[2:3]
	global_load_dwordx4 v[120:123], v[116:117], off
	s_nop 0
	global_load_dwordx4 v[116:119], v[2:3], off
	v_add_u32_e32 v2, 56, v124
	v_min_i32_e32 v3, s1, v2
	v_cmp_lt_i32_e32 vcc, -1, v2
	s_nop 1
	v_cndmask_b32_e32 v2, 0, v3, vcc
	v_lshlrev_b32_e32 v2, s0, v2
	v_add_u32_e32 v2, s20, v2
	v_lshl_or_b32 v2, v2, 6, v180
	v_ashrrev_i32_e32 v3, 31, v2
	v_lshlrev_b64 v[2:3], 1, v[2:3]
	v_lshl_add_u64 v[124:125], s[10:11], 0, v[2:3]
	v_lshl_add_u64 v[2:3], s[12:13], 0, v[2:3]
	global_load_dwordx4 v[128:131], v[124:125], off
	s_nop 0
	global_load_dwordx4 v[124:127], v[2:3], off
.Lrl_tail2:
	s_andn2_b64 vcc, exec, s[16:17]
	s_mov_b64 s[0:1], 0
	s_cbranch_vccnz .LBB0_564
	s_add_i32 s16, s76, 1
	s_cmp_lt_i32 s76, 2
	s_mov_b64 s[14:15], -1
	s_cbranch_scc1 .LBB0_563
	s_add_i32 s17, s75, 1
	s_cmp_lt_i32 s75, 2
	s_cselect_b64 s[14:15], -1, 0
	s_and_b64 s[20:21], s[14:15], exec
	s_cselect_b32 s16, s66, s16
	s_mov_b32 s75, s17

	.amdhsa_kernel _Z8mega_fwd4Args
		.amdhsa_group_segment_fixed_size 0
		.amdhsa_private_segment_fixed_size 0
		.amdhsa_kernarg_size 416
		.amdhsa_user_sgpr_count 2
		.amdhsa_user_sgpr_dispatch_ptr 0
		.amdhsa_user_sgpr_queue_ptr 0
		.amdhsa_user_sgpr_kernarg_segment_ptr 1
		.amdhsa_user_sgpr_dispatch_id 0
		.amdhsa_user_sgpr_kernarg_preload_length 0
		.amdhsa_user_sgpr_kernarg_preload_offset 0
		.amdhsa_user_sgpr_private_segment_size 0
		.amdhsa_uses_dynamic_stack 0
		.amdhsa_enable_private_segment 0
		.amdhsa_system_sgpr_workgroup_id_x 1
		.amdhsa_system_sgpr_workgroup_id_y 0
		.amdhsa_system_sgpr_workgroup_id_z 0
		.amdhsa_system_sgpr_workgroup_info 0
		.amdhsa_system_vgpr_workitem_id 2
		.amdhsa_next_free_vgpr 255
		.amdhsa_next_free_sgpr 100
		.amdhsa_accum_offset 256
		.amdhsa_reserve_vcc 1
		.amdhsa_float_round_mode_32 0
		.amdhsa_float_round_mode_16_64 0
		.amdhsa_float_denorm_mode_32 3
		.amdhsa_float_denorm_mode_16_64 3
		.amdhsa_dx10_clamp 1
		.amdhsa_ieee_mode 1
		.amdhsa_fp16_overflow 0
		.amdhsa_tg_split 0
		.amdhsa_exception_fp_ieee_invalid_op 0
		.amdhsa_exception_fp_denorm_src 0
		.amdhsa_exception_fp_ieee_div_zero 0
		.amdhsa_exception_fp_ieee_overflow 0
		.amdhsa_exception_fp_ieee_underflow 0
		.amdhsa_exception_fp_ieee_inexact 0
		.amdhsa_exception_int_div_zero 0
	.end_amdhsa_kernel

amdhsa.kernels:
  - .agpr_count:     0
    .args:
      - .offset:         0
        .size:           160
        .value_kind:     by_value
      - .offset:         160
        .size:           4
        .value_kind:     hidden_block_count_x
      - .offset:         164
        .size:           4
        .value_kind:     hidden_block_count_y
      - .offset:         168
        .size:           4
        .value_kind:     hidden_block_count_z
      - .offset:         172
        .size:           2
        .value_kind:     hidden_group_size_x
      - .offset:         174
        .size:           2
        .value_kind:     hidden_group_size_y
      - .offset:         176
        .size:           2
        .value_kind:     hidden_group_size_z
      - .offset:         178
        .size:           2
        .value_kind:     hidden_remainder_x
      - .offset:         180
        .size:           2
        .value_kind:     hidden_remainder_y
      - .offset:         182
        .size:           2
        .value_kind:     hidden_remainder_z
      - .offset:         200
        .size:           8
        .value_kind:     hidden_global_offset_x
      - .offset:         208
        .size:           8
        .value_kind:     hidden_global_offset_y
      - .offset:         216
        .size:           8
        .value_kind:     hidden_global_offset_z
      - .offset:         224
        .size:           2
        .value_kind:     hidden_grid_dims
      - .offset:         248
        .size:           8
        .value_kind:     hidden_multigrid_sync_arg
      - .offset:         280
        .size:           4
        .value_kind:     hidden_dynamic_lds_size
    .group_segment_fixed_size: 0
    .kernarg_segment_align: 8
    .kernarg_segment_size: 416
    .language:       OpenCL C
    .language_version:
      - 2
      - 0
    .max_flat_workgroup_size: 512
    .name:           _Z8mega_fwd4Args
    .private_segment_fixed_size: 0
    .sgpr_count:     106
    .sgpr_spill_count: 4
    .symbol:         _Z8mega_fwd4Args.kd
    .uniform_work_group_size: 1
    .uses_dynamic_stack: false
    .vgpr_count:     255
    .vgpr_spill_count: 0
    .wavefront_size: 64
